# LayerNorm rows prefetched two rows ahead through a per-wave LDS ring (global_load_lds), one row of stores in flight
# speedup vs baseline: 1.0141x; 1.0141x over previous
; #define GAS __attribute__((address_space(1)))
; __device__ __forceinline__ void phase_ln(const bool HAS_H, bf16_t* zx, float* dout, const float* g, const float* b, const float* scale, const float* shift, bf16_t* H, int lane, int wave) {
;     ...
;     u32x4 wn[4];
;     if (gw < SEQ) {
; #pragma unroll
;         for (int j = 0; j < 4; ++j) wn[j] = *(const GAS u32x4*)(zx + (size_t)gw * DM + 8 * lane + 512 * j); }
;     for (int row = gw; row < SEQ; row += NGW) { bf16_t* zr = zx + (size_t)row * DM + 8 * lane;
;         f32x4 v[8]; float s = 0.f;
;         u32x4 wc_[4];
; #pragma unroll
;         for (int j = 0; j < 4; ++j) wc_[j] = wn[j];
;         if (row + NGW < SEQ) {
; #pragma unroll
;             for (int j = 0; j < 4; ++j) wn[j] = *(const GAS u32x4*)(zr + (size_t)NGW * DM + 512 * j); }
.LBB0_222:
	s_add_i32 s6, s33, s73
	s_mov_b32 s20, s33
	s_cmpk_lt_i32 s6, 0x4000
	s_mov_b64 s[18:19], s[30:31]
	s_cbranch_scc0 .LBB0_243
	s_ashr_i32 s7, s6, 31
	s_xor_b64 s[14:15], s[14:15], -1
	s_lshl_b64 s[0:1], s[6:7], 12
	s_add_u32 s0, s86, s0
	s_addc_u32 s1, s87, s1
	s_add_u32 s0, s0, 0x1f000000
	s_addc_u32 s1, s1, 0
	v_lshlrev_b32_e32 v3, 1, v3
	global_load_dwordx4 v[116:119], v3, s[0:1] offset:3072
	global_load_dwordx4 v[120:123], v3, s[0:1] offset:2048
	global_load_dwordx4 v[124:127], v3, s[0:1] offset:1024
	global_load_dwordx4 v[128:131], v3, s[0:1]
	v_and_b32_e32 v3, 64, v225
	v_xor_b32_e32 v102, 1, v225
	v_add_u32_e32 v3, 64, v3
	v_xor_b32_e32 v103, 2, v225
	v_cmp_lt_i32_e32 vcc, v102, v3
	v_xor_b32_e32 v104, 4, v225
	v_xor_b32_e32 v105, 8, v225
	v_cndmask_b32_e32 v102, v225, v102, vcc
	v_cmp_lt_i32_e32 vcc, v103, v3
	v_xor_b32_e32 v106, 16, v225
	v_xor_b32_e32 v107, 32, v225
	v_cndmask_b32_e32 v103, v225, v103, vcc
	v_cmp_lt_i32_e32 vcc, v104, v3
	v_lshlrev_b32_e32 v100, 4, v134
	v_mov_b32_e32 v101, v2
	v_cndmask_b32_e32 v104, v225, v104, vcc
	v_cmp_lt_i32_e32 vcc, v105, v3
	s_lshl_b64 s[18:19], s[6:7], 13
	v_lshl_add_u64 v[170:171], s[0:1], 0, v[100:101]
	v_cndmask_b32_e32 v105, v225, v105, vcc
	v_cmp_lt_i32_e32 vcc, v106, v3
	v_lshl_or_b32 v100, v134, 5, s18
	v_mov_b32_e32 v101, s19
	v_cndmask_b32_e32 v106, v225, v106, vcc
	v_cmp_lt_i32_e32 vcc, v107, v3
	s_mov_b64 s[16:17], 0x1810
	v_lshl_add_u64 v[100:101], s[4:5], 0, v[100:101]
	v_cndmask_b32_e32 v107, v225, v107, vcc
	v_lshlrev_b32_e32 v3, 2, v102
	v_lshlrev_b32_e32 v133, 2, v103
	v_lshlrev_b32_e32 v135, 2, v104
	v_lshlrev_b32_e32 v206, 2, v105
	v_lshlrev_b32_e32 v208, 2, v106
	v_lshlrev_b32_e32 v210, 2, v107
	v_lshl_add_u64 v[168:169], v[100:101], 0, s[16:17]
	s_mov_b64 s[18:19], s[30:31]
	s_waitcnt vmcnt(3)
	v_mov_b64_e32 v[100:101], v[116:117]
	s_waitcnt vmcnt(2)
	v_mov_b64_e32 v[104:105], v[120:121]
	s_waitcnt vmcnt(1)
	v_mov_b64_e32 v[108:109], v[124:125]
	s_waitcnt vmcnt(0)
	v_mov_b64_e32 v[112:113], v[128:129]
	v_mov_b64_e32 v[102:103], v[118:119]
	v_mov_b64_e32 v[106:107], v[122:123]
	v_mov_b64_e32 v[110:111], v[126:127]
	v_mov_b64_e32 v[114:115], v[130:131]
	s_mul_i32 s101, s33, 0x3000
	s_add_u32 s100, s101, 0x1000
	s_add_u32 s101, s101, 0x3000
	s_add_i32 s0, s6, s94
	s_cmpk_gt_i32 s0, 0x3fff
	s_cbranch_scc1 .Lmy_ln_pre_done
	v_lshl_add_u64 v[100:101], v[170:171], 0, s[88:89]
	s_mov_b32 m0, s100
	s_nop 0
	global_load_lds_dwordx4 v[100:101], off
	global_load_lds_dwordx4 v[100:101], off offset:1024
	global_load_lds_dwordx4 v[100:101], off offset:2048
	global_load_lds_dwordx4 v[100:101], off offset:3072

; #define GAS __attribute__((address_space(1)))
; __device__ __forceinline__ void phase_ln(const bool HAS_H, bf16_t* zx, float* dout, const float* g, const float* b, const float* scale, const float* shift, bf16_t* H, int lane, int wave) {
;     ...
;     for (int row = gw; row < SEQ; row += NGW) { bf16_t* zr = zx + (size_t)row * DM + 8 * lane;
;         f32x4 v[8]; float s = 0.f;
;         u32x4 wc_[4];
; #pragma unroll
;         for (int j = 0; j < 4; ++j) wc_[j] = wn[j];
;         if (row + NGW < SEQ) {
; #pragma unroll
;             for (int j = 0; j < 4; ++j) wn[j] = *(const GAS u32x4*)(zr + (size_t)NGW * DM + 512 * j); }
.LBB0_224:
	s_lshl_b32 s0, s94, 1
	s_cmp_lt_u32 s6, s0
	s_cselect_b32 s0, 0, 8
	s_add_i32 s1, s6, s94
	s_cmpk_gt_i32 s1, 0x3fff
	s_cselect_b32 s1, 0, 4
	s_add_u32 s0, s0, s1
	s_cmp_eq_u32 s0, 12
	s_cbranch_scc1 .Lmy_ln_w20
	s_cmp_eq_u32 s0, 8
	s_cbranch_scc1 .Lmy_ln_w16
	s_cmp_eq_u32 s0, 4
	s_cbranch_scc1 .Lmy_ln_w12
	s_waitcnt vmcnt(8)
	s_branch .Lmy_ln_wdone
.Lmy_ln_w12:
	s_waitcnt vmcnt(12)
	s_branch .Lmy_ln_wdone
.Lmy_ln_w16:
	s_waitcnt vmcnt(8)
	s_branch .Lmy_ln_wdone
.Lmy_ln_w20:
	s_waitcnt vmcnt(12)
.Lmy_ln_wdone:
	v_lshlrev_b32_e32 v100, 4, v225
	v_add_u32_e32 v100, s100, v100
	ds_read_b128 v[128:131], v100
	ds_read_b128 v[124:127], v100 offset:1024
	ds_read_b128 v[120:123], v100 offset:2048
	ds_read_b128 v[116:119], v100 offset:3072
	s_add_u32 s100, s100, 0x1000
	s_cmp_eq_u32 s100, s101
	s_cbranch_scc0 .Lmy_ln_nw2
	s_sub_u32 s100, s101, 0x3000
.Lmy_ln_nw2:
	v_readlane_b32 s0, v252, 8
	v_readlane_b32 s1, v252, 9
	s_nop 3
	v_lshl_add_u64 v[168:169], v[168:169], 0, s[0:1]
	s_andn2_b64 vcc, exec, s[4:5]
	v_mov_b64_e32 v[170:171], v[172:173]
	s_waitcnt lgkmcnt(0)
	s_cbranch_vccz .LBB0_243
.LBB0_225:
	s_add_i32 s6, s6, s94
	s_cmpk_gt_i32 s6, 0x3fff
	s_cselect_b64 s[4:5], -1, 0
	v_lshl_add_u64 v[172:173], v[170:171], 0, s[88:89]
	s_add_i32 s0, s6, s94
	s_cmpk_gt_i32 s0, 0x3fff
	s_cbranch_scc1 .LBB0_227
	s_add_u32 s0, s100, 0x1000
	s_cmp_eq_u32 s0, s101
	s_cbranch_scc0 .Lmy_ln_nw1
	s_sub_u32 s0, s101, 0x3000
.Lmy_ln_nw1:
	v_lshl_add_u64 v[100:101], v[172:173], 0, s[88:89]
	s_mov_b32 m0, s0
	s_nop 0
	global_load_lds_dwordx4 v[100:101], off
	global_load_lds_dwordx4 v[100:101], off offset:1024
	global_load_lds_dwordx4 v[100:101], off offset:2048
	global_load_lds_dwordx4 v[100:101], off offset:3072

; __global__ void __launch_bounds__(NTHREADS, 2) mk_fwd(Params p) {
	.amdhsa_kernel _Z6mk_fwd6Params
		.amdhsa_group_segment_fixed_size 0
		.amdhsa_private_segment_fixed_size 0
		.amdhsa_kernarg_size 488
		.amdhsa_user_sgpr_count 2
		.amdhsa_user_sgpr_dispatch_ptr 0
		.amdhsa_user_sgpr_queue_ptr 0
		.amdhsa_user_sgpr_kernarg_segment_ptr 1
		.amdhsa_user_sgpr_dispatch_id 0
		.amdhsa_user_sgpr_kernarg_preload_length 0
		.amdhsa_user_sgpr_kernarg_preload_offset 0
		.amdhsa_user_sgpr_private_segment_size 0
		.amdhsa_uses_dynamic_stack 0
		.amdhsa_enable_private_segment 0
		.amdhsa_system_sgpr_workgroup_id_x 1
		.amdhsa_system_sgpr_workgroup_id_y 0
		.amdhsa_system_sgpr_workgroup_id_z 0
		.amdhsa_system_sgpr_workgroup_info 0
		.amdhsa_system_vgpr_workitem_id 2
		.amdhsa_next_free_vgpr 253
		.amdhsa_next_free_sgpr 102
		.amdhsa_accum_offset 256
		.amdhsa_reserve_vcc 1
		.amdhsa_float_round_mode_32 0
		.amdhsa_float_round_mode_16_64 0
		.amdhsa_float_denorm_mode_32 3
		.amdhsa_float_denorm_mode_16_64 3
		.amdhsa_dx10_clamp 1
		.amdhsa_ieee_mode 1
		.amdhsa_fp16_overflow 0
		.amdhsa_tg_split 0
		.amdhsa_exception_fp_ieee_invalid_op 0
		.amdhsa_exception_fp_denorm_src 0
		.amdhsa_exception_fp_ieee_div_zero 0
		.amdhsa_exception_fp_ieee_overflow 0
		.amdhsa_exception_fp_ieee_underflow 0
		.amdhsa_exception_fp_ieee_inexact 0
		.amdhsa_exception_int_div_zero 0
	.end_amdhsa_kernel

; __global__ void __launch_bounds__(NTHREADS, 2) mk_fwd(Params p) {
amdhsa.kernels:
  - .agpr_count:     0
    .args:
      - .offset:         0
        .size:           232
        .value_kind:     by_value
      - .offset:         232
        .size:           4
        .value_kind:     hidden_block_count_x
      - .offset:         236
        .size:           4
        .value_kind:     hidden_block_count_y
      - .offset:         240
        .size:           4
        .value_kind:     hidden_block_count_z
      - .offset:         244
        .size:           2
        .value_kind:     hidden_group_size_x
      - .offset:         246
        .size:           2
        .value_kind:     hidden_group_size_y
      - .offset:         248
        .size:           2
        .value_kind:     hidden_group_size_z
      - .offset:         250
        .size:           2
        .value_kind:     hidden_remainder_x
      - .offset:         252
        .size:           2
        .value_kind:     hidden_remainder_y
      - .offset:         254
        .size:           2
        .value_kind:     hidden_remainder_z
      - .offset:         272
        .size:           8
        .value_kind:     hidden_global_offset_x
      - .offset:         280
        .size:           8
        .value_kind:     hidden_global_offset_y
      - .offset:         288
        .size:           8
        .value_kind:     hidden_global_offset_z
      - .offset:         296
        .size:           2
        .value_kind:     hidden_grid_dims
      - .offset:         320
        .size:           8
        .value_kind:     hidden_multigrid_sync_arg
      - .offset:         352
        .size:           4
        .value_kind:     hidden_dynamic_lds_size
    .group_segment_fixed_size: 0
    .kernarg_segment_align: 8
    .kernarg_segment_size: 488
    .language:       OpenCL C
    .language_version:
      - 2
      - 0
    .max_flat_workgroup_size: 512
    .name:           _Z6mk_fwd6Params
    .private_segment_fixed_size: 0
    .sgpr_count:     108
    .sgpr_spill_count: 52
    .symbol:         _Z6mk_fwd6Params.kd
    .uniform_work_group_size: 1
    .uses_dynamic_stack: false
    .vgpr_count:     253
    .vgpr_spill_count: 0
    .wavefront_size: 64
